# SwiGLU epilogues: log2(e) folded into the gate rstd (exp2 takes the negated scaled gate), 64 multiplies per wave-tile removed; f32 math, same operations otherwise
# baseline (speedup 1.0000x reference)
; DI u32x4 pack8(f32x4 a, f32x4 b) { u32x4 w; w.x = pk2(a[0], a[1]); w.y = pk2(a[2], a[3]); w.z = pk2(b[0], b[1]); w.w = pk2(b[2], b[3]); return w; }
; #define EPI_ROWS(ai, m) _Pragma("unroll") for (int ai = 0; ai < 2; ++ai) _Pragma("unroll") for (int m = 0; m < 4; ++m)
; #define EPI_RSTD8(rr, ssqp, invn) float rr[2][4]; EPI_ROWS(ai, m) rr[ai][m] = (ssqp)[epi_row(u, ai, wr, m, fr)]; EPI_FENCE(); EPI_ROWS(ai, m) rr[ai][m] = rstd_of(rr[ai][m], invn);
; DI float sigm(float x) { return __builtin_amdgcn_rcpf(1.0f + __expf(-x)); }
; DI float silu(float x) { return x * sigm(x); }
; DI float rstd_of(float ssq, float invn) { return __builtin_amdgcn_rsqf(ssq * invn + EPS); }
;     DI void operator()(const Acc& acc, const Unit& u, int wr, int wc, int fr, int fq) const {
;         const int cb = u.pn * 128 + wc * 32 + 8 * fq;
;         EPI_RSTD8(rr, ssq, 1.0f / D)
;         EPI_ROWS(ai, m) { const int row = epi_row(u, ai, wr, m, fr); const float r = rr[ai][m];
;             f32x4 v[2];
; #pragma unroll
;             for (int n = 0; n < 2; ++n)
; #pragma unroll
;                 for (int j = 0; j < 4; ++j) v[n][j] = silu(acc[ai][0][m][n][j] * r) * (acc[ai][1][m][n][j] * r);
;             *(u32x4*)(act + (size_t)row * FF + cb) = pack8(v[0], v[1]); }
.LBB0_231:
	s_lshl_b32 s31, s40, 8
	s_add_i32 s31, s31, s95
	v_mbcnt_lo_u32_b32 v146, -1, 0
	v_mbcnt_hi_u32_b32 v146, -1, v146
	s_andn2_b64 vcc, exec, s[6:7]
	v_and_or_b32 v170, v146, 15, s31
	v_ashrrev_i32_e32 v171, 31, v170
	v_lshl_add_u64 v[144:145], v[170:171], 2, s[12:13]
	global_load_dword v150, v[144:145], off
	v_or_b32_e32 v168, 16, v170
	v_ashrrev_i32_e32 v169, 31, v168
	v_or_b32_e32 v164, 32, v170
	v_or_b32_e32 v160, 48, v170
	v_add_u32_e32 v156, 0x80, v170
	v_add_u32_e32 v152, 0x90, v170
	v_add_u32_e32 v148, 0xa0, v170
	v_add_u32_e32 v144, 0xb0, v170
	v_lshl_add_u64 v[166:167], v[168:169], 2, s[12:13]
	v_ashrrev_i32_e32 v165, 31, v164
	v_ashrrev_i32_e32 v161, 31, v160
	v_ashrrev_i32_e32 v157, 31, v156
	v_ashrrev_i32_e32 v153, 31, v152
	v_ashrrev_i32_e32 v149, 31, v148
	v_ashrrev_i32_e32 v145, 31, v144
	v_lshl_add_u64 v[172:173], v[164:165], 2, s[12:13]
	v_lshl_add_u64 v[174:175], v[160:161], 2, s[12:13]
	v_lshl_add_u64 v[176:177], v[156:157], 2, s[12:13]
	v_lshl_add_u64 v[178:179], v[152:153], 2, s[12:13]
	v_lshl_add_u64 v[180:181], v[148:149], 2, s[12:13]
	v_lshl_add_u64 v[182:183], v[144:145], 2, s[12:13]
	global_load_dword v145, v[166:167], off
	global_load_dword v149, v[172:173], off
	global_load_dword v153, v[174:175], off
	global_load_dword v154, v[176:177], off
	global_load_dword v157, v[178:179], off
	global_load_dword v158, v[180:181], off
	global_load_dword v161, v[182:183], off
	s_lshl_b32 s31, s58, 7
	v_ashrrev_i32_e32 v146, 1, v146
	s_or_b32 s31, s31, s22
	v_and_b32_e32 v146, -8, v146
	v_add_u32_e32 v172, s31, v146
	v_ashrrev_i32_e32 v173, 31, v172
	s_mov_b64 s[6:7], -1
	s_waitcnt vmcnt(0)
	v_fmamk_f32 v146, v150, 0x3a800000, v163
	v_rsq_f32_e32 v174, v146
	v_fmamk_f32 v145, v145, 0x3a800000, v163
	v_fmamk_f32 v146, v149, 0x3a800000, v163
	v_fmamk_f32 v149, v153, 0x3a800000, v163
	v_fmamk_f32 v150, v154, 0x3a800000, v163
	v_fmamk_f32 v153, v157, 0x3a800000, v163
	v_fmamk_f32 v157, v158, 0x3a800000, v163
	v_fmamk_f32 v161, v161, 0x3a800000, v163
	v_mul_f32_e32 v236, 0x3f317218, v174
	v_mul_f32_e32 v174, 0x3fb8aa3b, v174
	v_pk_mul_f32 v[124:125], v[124:125], v[174:175] op_sel_hi:[1,0]
	v_pk_mul_f32 v[126:127], v[126:127], v[174:175] op_sel_hi:[1,0]
	v_pk_mul_f32 v[120:121], v[120:121], v[174:175] op_sel_hi:[1,0]
	v_rsq_f32_e32 v176, v145
	v_rsq_f32_e32 v166, v146
	v_rsq_f32_e32 v162, v149
	v_rsq_f32_e32 v158, v150
	v_rsq_f32_e32 v154, v153
	v_rsq_f32_e32 v150, v157
	v_rsq_f32_e32 v146, v161
	s_nop 0
	v_mul_f32_e32 v238, 0x3f317218, v176
	v_mul_f32_e32 v240, 0x3f317218, v166
	v_mul_f32_e32 v242, 0x3f317218, v162
	v_mul_f32_e32 v244, 0x3f317218, v158
	v_mul_f32_e32 v246, 0x3f317218, v154
	v_mul_f32_e32 v248, 0x3f317218, v150
	v_mul_f32_e32 v250, 0x3f317218, v146
	v_mul_f32_e32 v176, 0x3fb8aa3b, v176
	v_mul_f32_e32 v166, 0x3fb8aa3b, v166
	v_mul_f32_e32 v162, 0x3fb8aa3b, v162
	v_mul_f32_e32 v158, 0x3fb8aa3b, v158
	v_mul_f32_e32 v154, 0x3fb8aa3b, v154
	v_mul_f32_e32 v150, 0x3fb8aa3b, v150
	v_mul_f32_e32 v146, 0x3fb8aa3b, v146
	v_pk_mul_f32 v[122:123], v[122:123], v[174:175] op_sel_hi:[1,0]
	v_exp_f32_e64 v145, -v124
	v_exp_f32_e64 v149, -v125
	v_exp_f32_e64 v153, -v126
	v_exp_f32_e64 v157, -v127
	v_exp_f32_e64 v161, -v120
	v_exp_f32_e64 v165, -v121
	v_exp_f32_e64 v167, -v122
	v_exp_f32_e64 v169, -v123
	v_add_f32_e32 v145, 1.0, v145
	v_add_f32_e32 v149, 1.0, v149
	v_add_f32_e32 v153, 1.0, v153
	v_add_f32_e32 v157, 1.0, v157
	v_add_f32_e32 v161, 1.0, v161
	v_add_f32_e32 v165, 1.0, v165
	v_add_f32_e32 v167, 1.0, v167
	v_add_f32_e32 v169, 1.0, v169
	v_rcp_f32_e32 v178, v145
	v_rcp_f32_e32 v179, v149
	v_rcp_f32_e32 v180, v153
	v_rcp_f32_e32 v181, v157
	v_rcp_f32_e32 v182, v161
	v_rcp_f32_e32 v183, v165
	v_rcp_f32_e32 v184, v167
	v_rcp_f32_e32 v185, v169
	v_pk_mul_f32 v[116:117], v[116:117], v[236:237] op_sel_hi:[1,0]
	v_pk_mul_f32 v[118:119], v[118:119], v[236:237] op_sel_hi:[1,0]
	v_pk_mul_f32 v[112:113], v[112:113], v[236:237] op_sel_hi:[1,0]
	v_pk_mul_f32 v[124:125], v[124:125], v[178:179]
	v_pk_mul_f32 v[126:127], v[126:127], v[180:181]
	v_pk_mul_f32 v[120:121], v[120:121], v[182:183]
	v_pk_mul_f32 v[116:117], v[116:117], v[124:125]
	v_pk_mul_f32 v[118:119], v[118:119], v[126:127]
	v_pk_mul_f32 v[112:113], v[112:113], v[120:121]
	v_pk_mul_f32 v[120:121], v[122:123], v[184:185]
	v_pk_mul_f32 v[114:115], v[114:115], v[236:237] op_sel_hi:[1,0]
	v_cvt_pk_bf16_f32 v116, v116, v117
	v_pk_mul_f32 v[114:115], v[114:115], v[120:121]
	v_cvt_pk_bf16_f32 v117, v118, v119
	v_cvt_pk_bf16_f32 v118, v112, v113
	v_mov_b64_e32 v[112:113], s[14:15]
	v_cvt_pk_bf16_f32 v119, v114, v115
	v_mad_i64_i32 v[120:121], s[42:43], v170, s55, v[112:113]
	v_lshlrev_b64 v[114:115], 1, v[172:173]
	v_pk_mul_f32 v[108:109], v[108:109], v[176:177] op_sel_hi:[1,0]
	v_lshl_add_u64 v[120:121], v[120:121], 0, v[114:115]
	v_pk_mul_f32 v[110:111], v[110:111], v[176:177] op_sel_hi:[1,0]
	v_exp_f32_e64 v122, -v108
	v_exp_f32_e64 v123, -v109
	global_store_dwordx4 v[120:121], v[116:119], off
	v_pk_mul_f32 v[100:101], v[100:101], v[238:239] op_sel_hi:[1,0]
	v_pk_mul_f32 v[104:105], v[104:105], v[176:177] op_sel_hi:[1,0]
	v_exp_f32_e64 v118, -v110
	v_exp_f32_e64 v119, -v111
	v_add_f32_e32 v116, 1.0, v122
	v_add_f32_e32 v117, 1.0, v123
	v_rcp_f32_e32 v116, v116
	v_rcp_f32_e32 v117, v117
	v_add_f32_e32 v118, 1.0, v118
	v_add_f32_e32 v119, 1.0, v119
	v_rcp_f32_e32 v118, v118
	v_rcp_f32_e32 v119, v119
	v_pk_mul_f32 v[108:109], v[108:109], v[116:117]
	v_pk_mul_f32 v[102:103], v[102:103], v[238:239] op_sel_hi:[1,0]
	v_pk_mul_f32 v[100:101], v[100:101], v[108:109]
	v_pk_mul_f32 v[108:109], v[110:111], v[118:119]
	v_exp_f32_e64 v110, -v104
	v_exp_f32_e64 v111, -v105
; DI u32x4 pack8(f32x4 a, f32x4 b) { u32x4 w; w.x = pk2(a[0], a[1]); w.y = pk2(a[2], a[3]); w.z = pk2(b[0], b[1]); w.w = pk2(b[2], b[3]); return w; }
; #define EPI_ROWS(ai, m) _Pragma("unroll") for (int ai = 0; ai < 2; ++ai) _Pragma("unroll") for (int m = 0; m < 4; ++m)
; DI float sigm(float x) { return __builtin_amdgcn_rcpf(1.0f + __expf(-x)); }
; DI float silu(float x) { return x * sigm(x); }
;     DI void operator()(const Acc& acc, const Unit& u, int wr, int wc, int fr, int fq) const {
;     ...
;         EPI_ROWS(ai, m) { const int row = epi_row(u, ai, wr, m, fr); const float r = rr[ai][m];
;             f32x4 v[2];
; #pragma unroll
;             for (int n = 0; n < 2; ++n)
; #pragma unroll
;                 for (int j = 0; j < 4; ++j) v[n][j] = silu(acc[ai][0][m][n][j] * r) * (acc[ai][1][m][n][j] * r);
;             *(u32x4*)(act + (size_t)row * FF + cb) = pack8(v[0], v[1]); }
	v_pk_mul_f32 v[106:107], v[106:107], v[176:177] op_sel_hi:[1,0]
	v_pk_mul_f32 v[102:103], v[102:103], v[108:109]
	v_add_f32_e32 v108, 1.0, v110
	v_add_f32_e32 v109, 1.0, v111
	v_exp_f32_e64 v110, -v106
	v_exp_f32_e64 v111, -v107
	v_rcp_f32_e32 v108, v108
	v_rcp_f32_e32 v109, v109
	v_add_f32_e32 v110, 1.0, v110
	v_add_f32_e32 v111, 1.0, v111
	v_rcp_f32_e32 v110, v110
	v_rcp_f32_e32 v111, v111
	v_pk_mul_f32 v[104:105], v[104:105], v[108:109]
	v_pk_mul_f32 v[96:97], v[96:97], v[238:239] op_sel_hi:[1,0]
	v_pk_mul_f32 v[98:99], v[98:99], v[238:239] op_sel_hi:[1,0]
	v_pk_mul_f32 v[104:105], v[96:97], v[104:105]
	v_pk_mul_f32 v[96:97], v[106:107], v[110:111]
	v_pk_mul_f32 v[92:93], v[92:93], v[166:167] op_sel_hi:[1,0]
	v_pk_mul_f32 v[106:107], v[98:99], v[96:97]
	v_cvt_pk_bf16_f32 v96, v100, v101
	v_mad_i64_i32 v[100:101], s[42:43], v168, s55, v[112:113]
	v_cvt_pk_bf16_f32 v97, v102, v103
	v_cvt_pk_bf16_f32 v98, v104, v105
	v_cvt_pk_bf16_f32 v99, v106, v107
	v_lshl_add_u64 v[100:101], v[100:101], 0, v[114:115]
	v_pk_mul_f32 v[94:95], v[94:95], v[166:167] op_sel_hi:[1,0]
	v_exp_f32_e64 v102, -v92
	v_exp_f32_e64 v103, -v93
	global_store_dwordx4 v[100:101], v[96:99], off
	v_pk_mul_f32 v[84:85], v[84:85], v[240:241] op_sel_hi:[1,0]
	v_pk_mul_f32 v[88:89], v[88:89], v[166:167] op_sel_hi:[1,0]
	v_exp_f32_e64 v98, -v94
	v_exp_f32_e64 v99, -v95
	v_add_f32_e32 v96, 1.0, v102
	v_add_f32_e32 v97, 1.0, v103
	v_rcp_f32_e32 v96, v96
	v_rcp_f32_e32 v97, v97
	v_add_f32_e32 v98, 1.0, v98
	v_add_f32_e32 v99, 1.0, v99
	v_rcp_f32_e32 v98, v98
	v_rcp_f32_e32 v99, v99
	v_pk_mul_f32 v[92:93], v[92:93], v[96:97]
	v_pk_mul_f32 v[86:87], v[86:87], v[240:241] op_sel_hi:[1,0]
	v_pk_mul_f32 v[84:85], v[84:85], v[92:93]
	v_pk_mul_f32 v[92:93], v[94:95], v[98:99]
	v_exp_f32_e64 v94, -v88
	v_exp_f32_e64 v95, -v89
	v_pk_mul_f32 v[90:91], v[90:91], v[166:167] op_sel_hi:[1,0]
	v_pk_mul_f32 v[86:87], v[86:87], v[92:93]
	v_add_f32_e32 v92, 1.0, v94
	v_add_f32_e32 v93, 1.0, v95
	v_exp_f32_e64 v94, -v90
	v_exp_f32_e64 v95, -v91
	v_rcp_f32_e32 v92, v92
	v_rcp_f32_e32 v93, v93
	v_add_f32_e32 v94, 1.0, v94
	v_add_f32_e32 v95, 1.0, v95
	v_rcp_f32_e32 v94, v94
	v_rcp_f32_e32 v95, v95
	v_pk_mul_f32 v[88:89], v[88:89], v[92:93]
	v_pk_mul_f32 v[80:81], v[80:81], v[240:241] op_sel_hi:[1,0]
	v_pk_mul_f32 v[82:83], v[82:83], v[240:241] op_sel_hi:[1,0]
	v_pk_mul_f32 v[88:89], v[80:81], v[88:89]
	v_pk_mul_f32 v[80:81], v[90:91], v[94:95]
	v_pk_mul_f32 v[76:77], v[76:77], v[162:163] op_sel_hi:[1,0]
	v_pk_mul_f32 v[90:91], v[82:83], v[80:81]
	v_cvt_pk_bf16_f32 v80, v84, v85
	v_mad_i64_i32 v[84:85], s[42:43], v164, s55, v[112:113]
	v_cvt_pk_bf16_f32 v81, v86, v87
	v_cvt_pk_bf16_f32 v82, v88, v89
	v_cvt_pk_bf16_f32 v83, v90, v91
	v_lshl_add_u64 v[84:85], v[84:85], 0, v[114:115]
	v_pk_mul_f32 v[78:79], v[78:79], v[162:163] op_sel_hi:[1,0]
	v_exp_f32_e64 v86, -v76
	v_exp_f32_e64 v87, -v77
	global_store_dwordx4 v[84:85], v[80:83], off
	v_pk_mul_f32 v[68:69], v[68:69], v[242:243] op_sel_hi:[1,0]
	v_pk_mul_f32 v[72:73], v[72:73], v[162:163] op_sel_hi:[1,0]
	v_exp_f32_e64 v82, -v78
	v_exp_f32_e64 v83, -v79
	v_add_f32_e32 v80, 1.0, v86
	v_add_f32_e32 v81, 1.0, v87
	v_rcp_f32_e32 v80, v80
	v_rcp_f32_e32 v81, v81
	v_add_f32_e32 v82, 1.0, v82
	v_add_f32_e32 v83, 1.0, v83
	v_rcp_f32_e32 v82, v82
	v_rcp_f32_e32 v83, v83
	v_pk_mul_f32 v[76:77], v[76:77], v[80:81]
	v_pk_mul_f32 v[70:71], v[70:71], v[242:243] op_sel_hi:[1,0]
	v_pk_mul_f32 v[68:69], v[68:69], v[76:77]
	v_pk_mul_f32 v[76:77], v[78:79], v[82:83]
	v_exp_f32_e64 v78, -v72
	v_exp_f32_e64 v79, -v73
	v_pk_mul_f32 v[74:75], v[74:75], v[162:163] op_sel_hi:[1,0]
	v_pk_mul_f32 v[70:71], v[70:71], v[76:77]
	v_add_f32_e32 v76, 1.0, v78
	v_add_f32_e32 v77, 1.0, v79
	v_exp_f32_e64 v78, -v74
	v_exp_f32_e64 v79, -v75
	v_rcp_f32_e32 v76, v76
	v_rcp_f32_e32 v77, v77
	v_add_f32_e32 v78, 1.0, v78
	v_add_f32_e32 v79, 1.0, v79
	v_rcp_f32_e32 v78, v78
	v_rcp_f32_e32 v79, v79
	v_pk_mul_f32 v[72:73], v[72:73], v[76:77]
	v_pk_mul_f32 v[64:65], v[64:65], v[242:243] op_sel_hi:[1,0]
	v_pk_mul_f32 v[66:67], v[66:67], v[242:243] op_sel_hi:[1,0]
	v_pk_mul_f32 v[72:73], v[64:65], v[72:73]
	v_pk_mul_f32 v[64:65], v[74:75], v[78:79]
	v_pk_mul_f32 v[60:61], v[60:61], v[158:159] op_sel_hi:[1,0]
	v_pk_mul_f32 v[74:75], v[66:67], v[64:65]
	v_cvt_pk_bf16_f32 v64, v68, v69
	v_mad_i64_i32 v[68:69], s[42:43], v160, s55, v[112:113]
	v_cvt_pk_bf16_f32 v65, v70, v71
	v_cvt_pk_bf16_f32 v66, v72, v73
	v_cvt_pk_bf16_f32 v67, v74, v75
	v_lshl_add_u64 v[68:69], v[68:69], 0, v[114:115]
	v_pk_mul_f32 v[62:63], v[62:63], v[158:159] op_sel_hi:[1,0]
	v_exp_f32_e64 v70, -v60
	v_exp_f32_e64 v71, -v61
	global_store_dwordx4 v[68:69], v[64:67], off
	v_pk_mul_f32 v[52:53], v[52:53], v[244:245] op_sel_hi:[1,0]
	v_pk_mul_f32 v[56:57], v[56:57], v[158:159] op_sel_hi:[1,0]
	v_exp_f32_e64 v66, -v62
	v_exp_f32_e64 v67, -v63
	v_add_f32_e32 v64, 1.0, v70
	v_add_f32_e32 v65, 1.0, v71
	v_rcp_f32_e32 v64, v64
	v_rcp_f32_e32 v65, v65
	v_add_f32_e32 v66, 1.0, v66
	v_add_f32_e32 v67, 1.0, v67
	v_rcp_f32_e32 v66, v66
	v_rcp_f32_e32 v67, v67
	v_pk_mul_f32 v[60:61], v[60:61], v[64:65]
	v_pk_mul_f32 v[54:55], v[54:55], v[244:245] op_sel_hi:[1,0]
	v_pk_mul_f32 v[52:53], v[52:53], v[60:61]
	v_pk_mul_f32 v[60:61], v[62:63], v[66:67]
	v_exp_f32_e64 v62, -v56
	v_exp_f32_e64 v63, -v57
	v_pk_mul_f32 v[58:59], v[58:59], v[158:159] op_sel_hi:[1,0]
	v_pk_mul_f32 v[54:55], v[54:55], v[60:61]
	v_add_f32_e32 v60, 1.0, v62
	v_add_f32_e32 v61, 1.0, v63
	v_exp_f32_e64 v62, -v58
	v_exp_f32_e64 v63, -v59
	v_rcp_f32_e32 v60, v60
	v_rcp_f32_e32 v61, v61
	v_add_f32_e32 v62, 1.0, v62
	v_add_f32_e32 v63, 1.0, v63
	v_rcp_f32_e32 v62, v62
; DI float silu(float x) { return x * sigm(x); }
; DI int lane_id() { int l; asm volatile("v_mbcnt_lo_u32_b32 %0, -1, 0\n\tv_mbcnt_hi_u32_b32 %0, -1, %0" : "=v"(l)); return l; }
; DI u32x4 pack8(f32x4 a, f32x4 b) { u32x4 w; w.x = pk2(a[0], a[1]); w.y = pk2(a[2], a[3]); w.z = pk2(b[0], b[1]); w.w = pk2(b[2], b[3]); return w; }
; #define PG8_BAR __builtin_amdgcn_s_barrier()
; #define EPI_ROWS(ai, m) _Pragma("unroll") for (int ai = 0; ai < 2; ++ai) _Pragma("unroll") for (int m = 0; m < 4; ++m)
; template <class Epi>
; DI void gemm_phase(LAS unsigned char* lds, const int wid, const Gemm g, const Order& S, const Epi& E) {
;     ...
;         if (wr == 0) PG8_BAR;
;         { const int le = lane_id(); E(acc, cur, wr, wc, le & 15, le >> 4); }
;         if (!has_next) break;
; #pragma unroll
;         for (int a = 0; a < 2; ++a)
; #pragma unroll
;             for (int b = 0; b < 2; ++b)
; #pragma unroll
;                 for (int m = 0; m < 4; ++m)
; #pragma unroll
;                     for (int n = 0; n < 2; ++n) acc[a][b][m][n] = (f32x4){0.f, 0.f, 0.f, 0.f};
;         cur = nxt; cA = nA; cB = nB; ++ui;
;         if (wr == 1) PG8_BAR;
;     DI void operator()(const Acc& acc, const Unit& u, int wr, int wc, int fr, int fq) const {
;     ...
;         EPI_ROWS(ai, m) { const int row = epi_row(u, ai, wr, m, fr); const float r = rr[ai][m];
;             f32x4 v[2];
; #pragma unroll
;             for (int n = 0; n < 2; ++n)
; #pragma unroll
;                 for (int j = 0; j < 4; ++j) v[n][j] = silu(acc[ai][0][m][n][j] * r) * (acc[ai][1][m][n][j] * r);
;             *(u32x4*)(act + (size_t)row * FF + cb) = pack8(v[0], v[1]); }
	v_rcp_f32_e32 v63, v63
	v_pk_mul_f32 v[56:57], v[56:57], v[60:61]
	v_pk_mul_f32 v[48:49], v[48:49], v[244:245] op_sel_hi:[1,0]
	v_pk_mul_f32 v[50:51], v[50:51], v[244:245] op_sel_hi:[1,0]
	v_pk_mul_f32 v[56:57], v[48:49], v[56:57]
	v_pk_mul_f32 v[48:49], v[58:59], v[62:63]
	v_pk_mul_f32 v[44:45], v[44:45], v[154:155] op_sel_hi:[1,0]
	v_pk_mul_f32 v[58:59], v[50:51], v[48:49]
	v_cvt_pk_bf16_f32 v48, v52, v53
	v_mad_i64_i32 v[52:53], s[42:43], v156, s55, v[112:113]
	v_cvt_pk_bf16_f32 v49, v54, v55
	v_cvt_pk_bf16_f32 v50, v56, v57
	v_cvt_pk_bf16_f32 v51, v58, v59
	v_lshl_add_u64 v[52:53], v[52:53], 0, v[114:115]
	v_pk_mul_f32 v[46:47], v[46:47], v[154:155] op_sel_hi:[1,0]
	v_exp_f32_e64 v54, -v44
	v_exp_f32_e64 v55, -v45
	global_store_dwordx4 v[52:53], v[48:51], off
	v_pk_mul_f32 v[36:37], v[36:37], v[246:247] op_sel_hi:[1,0]
	v_pk_mul_f32 v[40:41], v[40:41], v[154:155] op_sel_hi:[1,0]
	v_exp_f32_e64 v50, -v46
	v_exp_f32_e64 v51, -v47
	v_add_f32_e32 v48, 1.0, v54
	v_add_f32_e32 v49, 1.0, v55
	v_rcp_f32_e32 v48, v48
	v_rcp_f32_e32 v49, v49
	v_add_f32_e32 v50, 1.0, v50
	v_add_f32_e32 v51, 1.0, v51
	v_rcp_f32_e32 v50, v50
	v_rcp_f32_e32 v51, v51
	v_pk_mul_f32 v[44:45], v[44:45], v[48:49]
	v_pk_mul_f32 v[38:39], v[38:39], v[246:247] op_sel_hi:[1,0]
	v_pk_mul_f32 v[36:37], v[36:37], v[44:45]
	v_pk_mul_f32 v[44:45], v[46:47], v[50:51]
	v_exp_f32_e64 v46, -v40
	v_exp_f32_e64 v47, -v41
	v_pk_mul_f32 v[42:43], v[42:43], v[154:155] op_sel_hi:[1,0]
	v_pk_mul_f32 v[38:39], v[38:39], v[44:45]
	v_add_f32_e32 v44, 1.0, v46
	v_add_f32_e32 v45, 1.0, v47
	v_exp_f32_e64 v46, -v42
	v_exp_f32_e64 v47, -v43
	v_rcp_f32_e32 v44, v44
	v_rcp_f32_e32 v45, v45
	v_add_f32_e32 v46, 1.0, v46
	v_add_f32_e32 v47, 1.0, v47
	v_rcp_f32_e32 v46, v46
	v_rcp_f32_e32 v47, v47
	v_pk_mul_f32 v[40:41], v[40:41], v[44:45]
	v_pk_mul_f32 v[32:33], v[32:33], v[246:247] op_sel_hi:[1,0]
	v_pk_mul_f32 v[34:35], v[34:35], v[246:247] op_sel_hi:[1,0]
	v_pk_mul_f32 v[40:41], v[32:33], v[40:41]
	v_pk_mul_f32 v[32:33], v[42:43], v[46:47]
	v_pk_mul_f32 v[28:29], v[28:29], v[150:151] op_sel_hi:[1,0]
	v_pk_mul_f32 v[42:43], v[34:35], v[32:33]
	v_cvt_pk_bf16_f32 v32, v36, v37
	v_mad_i64_i32 v[36:37], s[42:43], v152, s55, v[112:113]
	v_cvt_pk_bf16_f32 v33, v38, v39
	v_cvt_pk_bf16_f32 v34, v40, v41
	v_cvt_pk_bf16_f32 v35, v42, v43
	v_lshl_add_u64 v[36:37], v[36:37], 0, v[114:115]
	v_pk_mul_f32 v[30:31], v[30:31], v[150:151] op_sel_hi:[1,0]
	v_exp_f32_e64 v38, -v28
	v_exp_f32_e64 v39, -v29
	global_store_dwordx4 v[36:37], v[32:35], off
	v_pk_mul_f32 v[20:21], v[20:21], v[248:249] op_sel_hi:[1,0]
	v_pk_mul_f32 v[24:25], v[24:25], v[150:151] op_sel_hi:[1,0]
	v_exp_f32_e64 v34, -v30
	v_exp_f32_e64 v35, -v31
	v_add_f32_e32 v32, 1.0, v38
	v_add_f32_e32 v33, 1.0, v39
	v_rcp_f32_e32 v32, v32
	v_rcp_f32_e32 v33, v33
	v_add_f32_e32 v34, 1.0, v34
	v_add_f32_e32 v35, 1.0, v35
	v_rcp_f32_e32 v34, v34
	v_rcp_f32_e32 v35, v35
	v_pk_mul_f32 v[28:29], v[28:29], v[32:33]
	v_pk_mul_f32 v[22:23], v[22:23], v[248:249] op_sel_hi:[1,0]
	v_pk_mul_f32 v[20:21], v[20:21], v[28:29]
	v_pk_mul_f32 v[28:29], v[30:31], v[34:35]
	v_exp_f32_e64 v30, -v24
	v_exp_f32_e64 v31, -v25
	v_pk_mul_f32 v[26:27], v[26:27], v[150:151] op_sel_hi:[1,0]
	v_pk_mul_f32 v[22:23], v[22:23], v[28:29]
	v_add_f32_e32 v28, 1.0, v30
	v_add_f32_e32 v29, 1.0, v31
	v_exp_f32_e64 v30, -v26
	v_exp_f32_e64 v31, -v27
	v_rcp_f32_e32 v28, v28
	v_rcp_f32_e32 v29, v29
	v_add_f32_e32 v30, 1.0, v30
	v_add_f32_e32 v31, 1.0, v31
	v_rcp_f32_e32 v30, v30
	v_rcp_f32_e32 v31, v31
	v_pk_mul_f32 v[24:25], v[24:25], v[28:29]
	v_pk_mul_f32 v[16:17], v[16:17], v[248:249] op_sel_hi:[1,0]
	v_pk_mul_f32 v[18:19], v[18:19], v[248:249] op_sel_hi:[1,0]
	v_pk_mul_f32 v[24:25], v[16:17], v[24:25]
	v_pk_mul_f32 v[16:17], v[26:27], v[30:31]
	v_pk_mul_f32 v[12:13], v[12:13], v[146:147] op_sel_hi:[1,0]
	v_pk_mul_f32 v[26:27], v[18:19], v[16:17]
	v_cvt_pk_bf16_f32 v16, v20, v21
	v_mad_i64_i32 v[20:21], s[42:43], v148, s55, v[112:113]
	v_cvt_pk_bf16_f32 v17, v22, v23
	v_cvt_pk_bf16_f32 v18, v24, v25
	v_cvt_pk_bf16_f32 v19, v26, v27
	v_lshl_add_u64 v[20:21], v[20:21], 0, v[114:115]
	v_pk_mul_f32 v[14:15], v[14:15], v[146:147] op_sel_hi:[1,0]
	v_exp_f32_e64 v22, -v12
	v_exp_f32_e64 v23, -v13
	global_store_dwordx4 v[20:21], v[16:19], off
	v_pk_mul_f32 v[4:5], v[4:5], v[250:251] op_sel_hi:[1,0]
	v_pk_mul_f32 v[8:9], v[8:9], v[146:147] op_sel_hi:[1,0]
	v_exp_f32_e64 v18, -v14
	v_exp_f32_e64 v19, -v15
	v_add_f32_e32 v16, 1.0, v22
	v_add_f32_e32 v17, 1.0, v23
	v_rcp_f32_e32 v16, v16
	v_rcp_f32_e32 v17, v17
	v_add_f32_e32 v18, 1.0, v18
	v_add_f32_e32 v19, 1.0, v19
	v_rcp_f32_e32 v18, v18
	v_rcp_f32_e32 v19, v19
	v_pk_mul_f32 v[12:13], v[12:13], v[16:17]
	v_pk_mul_f32 v[6:7], v[6:7], v[250:251] op_sel_hi:[1,0]
	v_pk_mul_f32 v[4:5], v[4:5], v[12:13]
	v_pk_mul_f32 v[12:13], v[14:15], v[18:19]
	v_exp_f32_e64 v14, -v8
	v_exp_f32_e64 v15, -v9
	v_pk_mul_f32 v[10:11], v[10:11], v[146:147] op_sel_hi:[1,0]
	v_pk_mul_f32 v[6:7], v[6:7], v[12:13]
	v_add_f32_e32 v12, 1.0, v14
	v_add_f32_e32 v13, 1.0, v15
	v_exp_f32_e64 v14, -v10
	v_exp_f32_e64 v15, -v11
	v_rcp_f32_e32 v12, v12
	v_rcp_f32_e32 v13, v13
	v_add_f32_e32 v14, 1.0, v14
	v_add_f32_e32 v15, 1.0, v15
	v_rcp_f32_e32 v14, v14
	v_rcp_f32_e32 v15, v15
	v_pk_mul_f32 v[8:9], v[8:9], v[12:13]
	v_pk_mul_f32 v[0:1], v[0:1], v[250:251] op_sel_hi:[1,0]
	v_pk_mul_f32 v[2:3], v[2:3], v[250:251] op_sel_hi:[1,0]
	v_pk_mul_f32 v[8:9], v[0:1], v[8:9]
	v_pk_mul_f32 v[0:1], v[10:11], v[14:15]
	s_nop 0
	v_pk_mul_f32 v[10:11], v[2:3], v[0:1]
	v_cvt_pk_bf16_f32 v0, v4, v5
	v_mad_i64_i32 v[4:5], s[42:43], v144, s55, v[112:113]
	v_cvt_pk_bf16_f32 v1, v6, v7
	v_cvt_pk_bf16_f32 v2, v8, v9
	v_cvt_pk_bf16_f32 v3, v10, v11
	v_lshl_add_u64 v[4:5], v[4:5], 0, v[114:115]
	global_store_dwordx4 v[4:5], v[0:3], off
	s_cbranch_vccnz .LBB0_224
	s_andn2_b64 vcc, exec, s[10:11]
	s_cbranch_vccnz .LBB0_223
	s_barrier
	s_branch .LBB0_223

; DI u32x4 pack8(f32x4 a, f32x4 b) { u32x4 w; w.x = pk2(a[0], a[1]); w.y = pk2(a[2], a[3]); w.z = pk2(b[0], b[1]); w.w = pk2(b[2], b[3]); return w; }
; #define EPI_ROWS(ai, m) _Pragma("unroll") for (int ai = 0; ai < 2; ++ai) _Pragma("unroll") for (int m = 0; m < 4; ++m)
; #define EPI_RSTD8(rr, ssqp, invn) float rr[2][4]; EPI_ROWS(ai, m) rr[ai][m] = (ssqp)[epi_row(u, ai, wr, m, fr)]; EPI_FENCE(); EPI_ROWS(ai, m) rr[ai][m] = rstd_of(rr[ai][m], invn);
; DI float sigm(float x) { return __builtin_amdgcn_rcpf(1.0f + __expf(-x)); }
; DI float silu(float x) { return x * sigm(x); }
; DI float rstd_of(float ssq, float invn) { return __builtin_amdgcn_rsqf(ssq * invn + EPS); }
;     DI void operator()(const Acc& acc, const Unit& u, int wr, int wc, int fr, int fq) const {
;         const int cb = u.pn * 128 + wc * 32 + 8 * fq;
;         EPI_RSTD8(rr, ssq, 1.0f / D)
;         EPI_ROWS(ai, m) { const int row = epi_row(u, ai, wr, m, fr); const float r = rr[ai][m];
;             f32x4 v[2];
; #pragma unroll
;             for (int n = 0; n < 2; ++n)
; #pragma unroll
;                 for (int j = 0; j < 4; ++j) v[n][j] = silu(acc[ai][0][m][n][j] * r) * (acc[ai][1][m][n][j] * r);
;             *(u32x4*)(act + (size_t)row * FF + cb) = pack8(v[0], v[1]); }
.LBB0_1339:
	s_lshl_b32 s27, s36, 8
	s_add_i32 s27, s27, s95
	v_mbcnt_lo_u32_b32 v146, -1, 0
	v_mbcnt_hi_u32_b32 v146, -1, v146
	s_andn2_b64 vcc, exec, s[8:9]
	v_and_or_b32 v170, v146, 15, s27
	v_ashrrev_i32_e32 v171, 31, v170
	v_lshl_add_u64 v[144:145], v[170:171], 2, s[12:13]
	global_load_dword v150, v[144:145], off
	v_or_b32_e32 v168, 16, v170
	v_ashrrev_i32_e32 v169, 31, v168
	v_or_b32_e32 v164, 32, v170
	v_or_b32_e32 v160, 48, v170
	v_add_u32_e32 v156, 0x80, v170
	v_add_u32_e32 v152, 0x90, v170
	v_add_u32_e32 v148, 0xa0, v170
	v_add_u32_e32 v144, 0xb0, v170
	v_lshl_add_u64 v[166:167], v[168:169], 2, s[12:13]
	v_ashrrev_i32_e32 v165, 31, v164
	v_ashrrev_i32_e32 v161, 31, v160
	v_ashrrev_i32_e32 v157, 31, v156
	v_ashrrev_i32_e32 v153, 31, v152
	v_ashrrev_i32_e32 v149, 31, v148
	v_ashrrev_i32_e32 v145, 31, v144
	v_lshl_add_u64 v[172:173], v[164:165], 2, s[12:13]
	v_lshl_add_u64 v[174:175], v[160:161], 2, s[12:13]
	v_lshl_add_u64 v[176:177], v[156:157], 2, s[12:13]
	v_lshl_add_u64 v[178:179], v[152:153], 2, s[12:13]
	v_lshl_add_u64 v[180:181], v[148:149], 2, s[12:13]
	v_lshl_add_u64 v[182:183], v[144:145], 2, s[12:13]
	global_load_dword v145, v[166:167], off
	global_load_dword v149, v[172:173], off
	global_load_dword v153, v[174:175], off
	global_load_dword v154, v[176:177], off
	global_load_dword v157, v[178:179], off
	global_load_dword v158, v[180:181], off
	global_load_dword v161, v[182:183], off
	s_lshl_b32 s27, s55, 7
	v_ashrrev_i32_e32 v146, 1, v146
	s_or_b32 s27, s27, s22
	v_and_b32_e32 v146, -8, v146
	v_add_u32_e32 v172, s27, v146
	v_ashrrev_i32_e32 v173, 31, v172
	s_mov_b64 s[8:9], -1
	s_waitcnt vmcnt(0)
	v_fmamk_f32 v146, v150, 0x3a800000, v163
	v_rsq_f32_e32 v174, v146
	v_fmamk_f32 v145, v145, 0x3a800000, v163
	v_fmamk_f32 v146, v149, 0x3a800000, v163
	v_fmamk_f32 v149, v153, 0x3a800000, v163
	v_fmamk_f32 v150, v154, 0x3a800000, v163
	v_fmamk_f32 v153, v157, 0x3a800000, v163
	v_fmamk_f32 v157, v158, 0x3a800000, v163
	v_fmamk_f32 v161, v161, 0x3a800000, v163
	v_mul_f32_e32 v236, 0x3f317218, v174
	v_mul_f32_e32 v174, 0x3fb8aa3b, v174
	v_pk_mul_f32 v[124:125], v[124:125], v[174:175] op_sel_hi:[1,0]
	v_pk_mul_f32 v[126:127], v[126:127], v[174:175] op_sel_hi:[1,0]
	v_pk_mul_f32 v[120:121], v[120:121], v[174:175] op_sel_hi:[1,0]
	v_rsq_f32_e32 v176, v145
	v_rsq_f32_e32 v166, v146
	v_rsq_f32_e32 v162, v149
	v_rsq_f32_e32 v158, v150
	v_rsq_f32_e32 v154, v153
	v_rsq_f32_e32 v150, v157
	v_rsq_f32_e32 v146, v161
	s_nop 0
	v_mul_f32_e32 v238, 0x3f317218, v176
	v_mul_f32_e32 v240, 0x3f317218, v166
	v_mul_f32_e32 v242, 0x3f317218, v162
	v_mul_f32_e32 v244, 0x3f317218, v158
	v_mul_f32_e32 v246, 0x3f317218, v154
	v_mul_f32_e32 v248, 0x3f317218, v150
	v_mul_f32_e32 v250, 0x3f317218, v146
	v_mul_f32_e32 v176, 0x3fb8aa3b, v176
	v_mul_f32_e32 v166, 0x3fb8aa3b, v166
	v_mul_f32_e32 v162, 0x3fb8aa3b, v162
	v_mul_f32_e32 v158, 0x3fb8aa3b, v158
	v_mul_f32_e32 v154, 0x3fb8aa3b, v154
	v_mul_f32_e32 v150, 0x3fb8aa3b, v150
	v_mul_f32_e32 v146, 0x3fb8aa3b, v146
	v_pk_mul_f32 v[122:123], v[122:123], v[174:175] op_sel_hi:[1,0]
	v_exp_f32_e64 v145, -v124
	v_exp_f32_e64 v149, -v125
	v_exp_f32_e64 v153, -v126
	v_exp_f32_e64 v157, -v127
	v_exp_f32_e64 v161, -v120
	v_exp_f32_e64 v165, -v121
	v_exp_f32_e64 v167, -v122
	v_exp_f32_e64 v169, -v123
	v_add_f32_e32 v145, 1.0, v145
	v_add_f32_e32 v149, 1.0, v149
	v_add_f32_e32 v153, 1.0, v153
	v_add_f32_e32 v157, 1.0, v157
	v_add_f32_e32 v161, 1.0, v161
	v_add_f32_e32 v165, 1.0, v165
	v_add_f32_e32 v167, 1.0, v167
	v_add_f32_e32 v169, 1.0, v169
	v_rcp_f32_e32 v178, v145
	v_rcp_f32_e32 v179, v149
	v_rcp_f32_e32 v180, v153
	v_rcp_f32_e32 v181, v157
	v_rcp_f32_e32 v182, v161
	v_rcp_f32_e32 v183, v165
	v_rcp_f32_e32 v184, v167
	v_rcp_f32_e32 v185, v169
	v_pk_mul_f32 v[116:117], v[116:117], v[236:237] op_sel_hi:[1,0]
	v_pk_mul_f32 v[118:119], v[118:119], v[236:237] op_sel_hi:[1,0]
	v_pk_mul_f32 v[112:113], v[112:113], v[236:237] op_sel_hi:[1,0]
	v_pk_mul_f32 v[124:125], v[124:125], v[178:179]
	v_pk_mul_f32 v[126:127], v[126:127], v[180:181]
	v_pk_mul_f32 v[120:121], v[120:121], v[182:183]
	v_pk_mul_f32 v[116:117], v[116:117], v[124:125]
	v_pk_mul_f32 v[118:119], v[118:119], v[126:127]
	v_pk_mul_f32 v[112:113], v[112:113], v[120:121]
	v_pk_mul_f32 v[120:121], v[122:123], v[184:185]
	v_pk_mul_f32 v[114:115], v[114:115], v[236:237] op_sel_hi:[1,0]
	v_cvt_pk_bf16_f32 v116, v116, v117
	v_pk_mul_f32 v[114:115], v[114:115], v[120:121]
	v_cvt_pk_bf16_f32 v117, v118, v119
	v_cvt_pk_bf16_f32 v118, v112, v113
	v_mov_b64_e32 v[112:113], s[14:15]
	v_cvt_pk_bf16_f32 v119, v114, v115
	v_mad_i64_i32 v[120:121], s[38:39], v170, s49, v[112:113]
	v_lshlrev_b64 v[114:115], 1, v[172:173]
	v_pk_mul_f32 v[108:109], v[108:109], v[176:177] op_sel_hi:[1,0]
	v_lshl_add_u64 v[120:121], v[120:121], 0, v[114:115]
	v_pk_mul_f32 v[110:111], v[110:111], v[176:177] op_sel_hi:[1,0]
	v_exp_f32_e64 v122, -v108
	v_exp_f32_e64 v123, -v109
	global_store_dwordx4 v[120:121], v[116:119], off
	v_pk_mul_f32 v[100:101], v[100:101], v[238:239] op_sel_hi:[1,0]
	v_pk_mul_f32 v[104:105], v[104:105], v[176:177] op_sel_hi:[1,0]
	v_exp_f32_e64 v118, -v110
	v_exp_f32_e64 v119, -v111
	v_add_f32_e32 v116, 1.0, v122
	v_add_f32_e32 v117, 1.0, v123
	v_rcp_f32_e32 v116, v116
	v_rcp_f32_e32 v117, v117
	v_add_f32_e32 v118, 1.0, v118
	v_add_f32_e32 v119, 1.0, v119
	v_rcp_f32_e32 v118, v118
	v_rcp_f32_e32 v119, v119
	v_pk_mul_f32 v[108:109], v[108:109], v[116:117]
	v_pk_mul_f32 v[102:103], v[102:103], v[238:239] op_sel_hi:[1,0]
	v_pk_mul_f32 v[100:101], v[100:101], v[108:109]
	v_pk_mul_f32 v[108:109], v[110:111], v[118:119]
	v_exp_f32_e64 v110, -v104
	v_exp_f32_e64 v111, -v105
; DI u32x4 pack8(f32x4 a, f32x4 b) { u32x4 w; w.x = pk2(a[0], a[1]); w.y = pk2(a[2], a[3]); w.z = pk2(b[0], b[1]); w.w = pk2(b[2], b[3]); return w; }
; #define EPI_ROWS(ai, m) _Pragma("unroll") for (int ai = 0; ai < 2; ++ai) _Pragma("unroll") for (int m = 0; m < 4; ++m)
; DI float sigm(float x) { return __builtin_amdgcn_rcpf(1.0f + __expf(-x)); }
; DI float silu(float x) { return x * sigm(x); }
;     DI void operator()(const Acc& acc, const Unit& u, int wr, int wc, int fr, int fq) const {
;     ...
;         EPI_ROWS(ai, m) { const int row = epi_row(u, ai, wr, m, fr); const float r = rr[ai][m];
;             f32x4 v[2];
; #pragma unroll
;             for (int n = 0; n < 2; ++n)
; #pragma unroll
;                 for (int j = 0; j < 4; ++j) v[n][j] = silu(acc[ai][0][m][n][j] * r) * (acc[ai][1][m][n][j] * r);
;             *(u32x4*)(act + (size_t)row * FF + cb) = pack8(v[0], v[1]); }
	v_pk_mul_f32 v[106:107], v[106:107], v[176:177] op_sel_hi:[1,0]
	v_pk_mul_f32 v[102:103], v[102:103], v[108:109]
	v_add_f32_e32 v108, 1.0, v110
	v_add_f32_e32 v109, 1.0, v111
	v_exp_f32_e64 v110, -v106
	v_exp_f32_e64 v111, -v107
	v_rcp_f32_e32 v108, v108
	v_rcp_f32_e32 v109, v109
	v_add_f32_e32 v110, 1.0, v110
	v_add_f32_e32 v111, 1.0, v111
	v_rcp_f32_e32 v110, v110
	v_rcp_f32_e32 v111, v111
	v_pk_mul_f32 v[104:105], v[104:105], v[108:109]
	v_pk_mul_f32 v[96:97], v[96:97], v[238:239] op_sel_hi:[1,0]
	v_pk_mul_f32 v[98:99], v[98:99], v[238:239] op_sel_hi:[1,0]
	v_pk_mul_f32 v[104:105], v[96:97], v[104:105]
	v_pk_mul_f32 v[96:97], v[106:107], v[110:111]
	v_pk_mul_f32 v[92:93], v[92:93], v[166:167] op_sel_hi:[1,0]
	v_pk_mul_f32 v[106:107], v[98:99], v[96:97]
	v_cvt_pk_bf16_f32 v96, v100, v101
	v_mad_i64_i32 v[100:101], s[38:39], v168, s49, v[112:113]
	v_cvt_pk_bf16_f32 v97, v102, v103
	v_cvt_pk_bf16_f32 v98, v104, v105
	v_cvt_pk_bf16_f32 v99, v106, v107
	v_lshl_add_u64 v[100:101], v[100:101], 0, v[114:115]
	v_pk_mul_f32 v[94:95], v[94:95], v[166:167] op_sel_hi:[1,0]
	v_exp_f32_e64 v102, -v92
	v_exp_f32_e64 v103, -v93
	global_store_dwordx4 v[100:101], v[96:99], off
	v_pk_mul_f32 v[84:85], v[84:85], v[240:241] op_sel_hi:[1,0]
	v_pk_mul_f32 v[88:89], v[88:89], v[166:167] op_sel_hi:[1,0]
	v_exp_f32_e64 v98, -v94
	v_exp_f32_e64 v99, -v95
	v_add_f32_e32 v96, 1.0, v102
	v_add_f32_e32 v97, 1.0, v103
	v_rcp_f32_e32 v96, v96
	v_rcp_f32_e32 v97, v97
	v_add_f32_e32 v98, 1.0, v98
	v_add_f32_e32 v99, 1.0, v99
	v_rcp_f32_e32 v98, v98
	v_rcp_f32_e32 v99, v99
	v_pk_mul_f32 v[92:93], v[92:93], v[96:97]
	v_pk_mul_f32 v[86:87], v[86:87], v[240:241] op_sel_hi:[1,0]
	v_pk_mul_f32 v[84:85], v[84:85], v[92:93]
	v_pk_mul_f32 v[92:93], v[94:95], v[98:99]
	v_exp_f32_e64 v94, -v88
	v_exp_f32_e64 v95, -v89
	v_pk_mul_f32 v[90:91], v[90:91], v[166:167] op_sel_hi:[1,0]
	v_pk_mul_f32 v[86:87], v[86:87], v[92:93]
	v_add_f32_e32 v92, 1.0, v94
	v_add_f32_e32 v93, 1.0, v95
	v_exp_f32_e64 v94, -v90
	v_exp_f32_e64 v95, -v91
	v_rcp_f32_e32 v92, v92
	v_rcp_f32_e32 v93, v93
	v_add_f32_e32 v94, 1.0, v94
	v_add_f32_e32 v95, 1.0, v95
	v_rcp_f32_e32 v94, v94
	v_rcp_f32_e32 v95, v95
	v_pk_mul_f32 v[88:89], v[88:89], v[92:93]
	v_pk_mul_f32 v[80:81], v[80:81], v[240:241] op_sel_hi:[1,0]
	v_pk_mul_f32 v[82:83], v[82:83], v[240:241] op_sel_hi:[1,0]
	v_pk_mul_f32 v[88:89], v[80:81], v[88:89]
	v_pk_mul_f32 v[80:81], v[90:91], v[94:95]
	v_pk_mul_f32 v[76:77], v[76:77], v[162:163] op_sel_hi:[1,0]
	v_pk_mul_f32 v[90:91], v[82:83], v[80:81]
	v_cvt_pk_bf16_f32 v80, v84, v85
	v_mad_i64_i32 v[84:85], s[38:39], v164, s49, v[112:113]
	v_cvt_pk_bf16_f32 v81, v86, v87
	v_cvt_pk_bf16_f32 v82, v88, v89
	v_cvt_pk_bf16_f32 v83, v90, v91
	v_lshl_add_u64 v[84:85], v[84:85], 0, v[114:115]
	v_pk_mul_f32 v[78:79], v[78:79], v[162:163] op_sel_hi:[1,0]
	v_exp_f32_e64 v86, -v76
	v_exp_f32_e64 v87, -v77
	global_store_dwordx4 v[84:85], v[80:83], off
	v_pk_mul_f32 v[68:69], v[68:69], v[242:243] op_sel_hi:[1,0]
	v_pk_mul_f32 v[72:73], v[72:73], v[162:163] op_sel_hi:[1,0]
	v_exp_f32_e64 v82, -v78
	v_exp_f32_e64 v83, -v79
	v_add_f32_e32 v80, 1.0, v86
	v_add_f32_e32 v81, 1.0, v87
	v_rcp_f32_e32 v80, v80
	v_rcp_f32_e32 v81, v81
	v_add_f32_e32 v82, 1.0, v82
	v_add_f32_e32 v83, 1.0, v83
	v_rcp_f32_e32 v82, v82
	v_rcp_f32_e32 v83, v83
	v_pk_mul_f32 v[76:77], v[76:77], v[80:81]
	v_pk_mul_f32 v[70:71], v[70:71], v[242:243] op_sel_hi:[1,0]
	v_pk_mul_f32 v[68:69], v[68:69], v[76:77]
	v_pk_mul_f32 v[76:77], v[78:79], v[82:83]
	v_exp_f32_e64 v78, -v72
	v_exp_f32_e64 v79, -v73
	v_pk_mul_f32 v[74:75], v[74:75], v[162:163] op_sel_hi:[1,0]
	v_pk_mul_f32 v[70:71], v[70:71], v[76:77]
	v_add_f32_e32 v76, 1.0, v78
	v_add_f32_e32 v77, 1.0, v79
	v_exp_f32_e64 v78, -v74
	v_exp_f32_e64 v79, -v75
	v_rcp_f32_e32 v76, v76
	v_rcp_f32_e32 v77, v77
	v_add_f32_e32 v78, 1.0, v78
	v_add_f32_e32 v79, 1.0, v79
	v_rcp_f32_e32 v78, v78
	v_rcp_f32_e32 v79, v79
	v_pk_mul_f32 v[72:73], v[72:73], v[76:77]
	v_pk_mul_f32 v[64:65], v[64:65], v[242:243] op_sel_hi:[1,0]
	v_pk_mul_f32 v[66:67], v[66:67], v[242:243] op_sel_hi:[1,0]
	v_pk_mul_f32 v[72:73], v[64:65], v[72:73]
	v_pk_mul_f32 v[64:65], v[74:75], v[78:79]
	v_pk_mul_f32 v[60:61], v[60:61], v[158:159] op_sel_hi:[1,0]
	v_pk_mul_f32 v[74:75], v[66:67], v[64:65]
	v_cvt_pk_bf16_f32 v64, v68, v69
	v_mad_i64_i32 v[68:69], s[38:39], v160, s49, v[112:113]
	v_cvt_pk_bf16_f32 v65, v70, v71
	v_cvt_pk_bf16_f32 v66, v72, v73
	v_cvt_pk_bf16_f32 v67, v74, v75
	v_lshl_add_u64 v[68:69], v[68:69], 0, v[114:115]
	v_pk_mul_f32 v[62:63], v[62:63], v[158:159] op_sel_hi:[1,0]
	v_exp_f32_e64 v70, -v60
	v_exp_f32_e64 v71, -v61
	global_store_dwordx4 v[68:69], v[64:67], off
	v_pk_mul_f32 v[52:53], v[52:53], v[244:245] op_sel_hi:[1,0]
	v_pk_mul_f32 v[56:57], v[56:57], v[158:159] op_sel_hi:[1,0]
	v_exp_f32_e64 v66, -v62
	v_exp_f32_e64 v67, -v63
	v_add_f32_e32 v64, 1.0, v70
	v_add_f32_e32 v65, 1.0, v71
	v_rcp_f32_e32 v64, v64
	v_rcp_f32_e32 v65, v65
	v_add_f32_e32 v66, 1.0, v66
	v_add_f32_e32 v67, 1.0, v67
	v_rcp_f32_e32 v66, v66
	v_rcp_f32_e32 v67, v67
	v_pk_mul_f32 v[60:61], v[60:61], v[64:65]
	v_pk_mul_f32 v[54:55], v[54:55], v[244:245] op_sel_hi:[1,0]
	v_pk_mul_f32 v[52:53], v[52:53], v[60:61]
	v_pk_mul_f32 v[60:61], v[62:63], v[66:67]
	v_exp_f32_e64 v62, -v56
	v_exp_f32_e64 v63, -v57
	v_pk_mul_f32 v[58:59], v[58:59], v[158:159] op_sel_hi:[1,0]
	v_pk_mul_f32 v[54:55], v[54:55], v[60:61]
	v_add_f32_e32 v60, 1.0, v62
	v_add_f32_e32 v61, 1.0, v63
	v_exp_f32_e64 v62, -v58
	v_exp_f32_e64 v63, -v59
	v_rcp_f32_e32 v60, v60
	v_rcp_f32_e32 v61, v61
	v_add_f32_e32 v62, 1.0, v62
	v_add_f32_e32 v63, 1.0, v63
	v_rcp_f32_e32 v62, v62
; DI float silu(float x) { return x * sigm(x); }
; DI u32x4 pack8(f32x4 a, f32x4 b) { u32x4 w; w.x = pk2(a[0], a[1]); w.y = pk2(a[2], a[3]); w.z = pk2(b[0], b[1]); w.w = pk2(b[2], b[3]); return w; }
; #define PG8_BAR __builtin_amdgcn_s_barrier()
; #define EPI_ROWS(ai, m) _Pragma("unroll") for (int ai = 0; ai < 2; ++ai) _Pragma("unroll") for (int m = 0; m < 4; ++m)
; template <class Epi>
; DI void gemm_phase(LAS unsigned char* lds, const int wid, const Gemm g, const Order& S, const Epi& E) {
;     ...
;         if (!has_next) break;
; #pragma unroll
;         for (int a = 0; a < 2; ++a)
; #pragma unroll
;             for (int b = 0; b < 2; ++b)
; #pragma unroll
;                 for (int m = 0; m < 4; ++m)
; #pragma unroll
;                     for (int n = 0; n < 2; ++n) acc[a][b][m][n] = (f32x4){0.f, 0.f, 0.f, 0.f};
;         cur = nxt; cA = nA; cB = nB; ++ui;
;         if (wr == 1) PG8_BAR;
;     DI void operator()(const Acc& acc, const Unit& u, int wr, int wc, int fr, int fq) const {
;     ...
;         EPI_ROWS(ai, m) { const int row = epi_row(u, ai, wr, m, fr); const float r = rr[ai][m];
;             f32x4 v[2];
; #pragma unroll
;             for (int n = 0; n < 2; ++n)
; #pragma unroll
;                 for (int j = 0; j < 4; ++j) v[n][j] = silu(acc[ai][0][m][n][j] * r) * (acc[ai][1][m][n][j] * r);
;             *(u32x4*)(act + (size_t)row * FF + cb) = pack8(v[0], v[1]); }
	v_rcp_f32_e32 v63, v63
	v_pk_mul_f32 v[56:57], v[56:57], v[60:61]
	v_pk_mul_f32 v[48:49], v[48:49], v[244:245] op_sel_hi:[1,0]
	v_pk_mul_f32 v[50:51], v[50:51], v[244:245] op_sel_hi:[1,0]
	v_pk_mul_f32 v[56:57], v[48:49], v[56:57]
	v_pk_mul_f32 v[48:49], v[58:59], v[62:63]
	v_pk_mul_f32 v[44:45], v[44:45], v[154:155] op_sel_hi:[1,0]
	v_pk_mul_f32 v[58:59], v[50:51], v[48:49]
	v_cvt_pk_bf16_f32 v48, v52, v53
	v_mad_i64_i32 v[52:53], s[38:39], v156, s49, v[112:113]
	v_cvt_pk_bf16_f32 v49, v54, v55
	v_cvt_pk_bf16_f32 v50, v56, v57
	v_cvt_pk_bf16_f32 v51, v58, v59
	v_lshl_add_u64 v[52:53], v[52:53], 0, v[114:115]
	v_pk_mul_f32 v[46:47], v[46:47], v[154:155] op_sel_hi:[1,0]
	v_exp_f32_e64 v54, -v44
	v_exp_f32_e64 v55, -v45
	global_store_dwordx4 v[52:53], v[48:51], off
	v_pk_mul_f32 v[36:37], v[36:37], v[246:247] op_sel_hi:[1,0]
	v_pk_mul_f32 v[40:41], v[40:41], v[154:155] op_sel_hi:[1,0]
	v_exp_f32_e64 v50, -v46
	v_exp_f32_e64 v51, -v47
	v_add_f32_e32 v48, 1.0, v54
	v_add_f32_e32 v49, 1.0, v55
	v_rcp_f32_e32 v48, v48
	v_rcp_f32_e32 v49, v49
	v_add_f32_e32 v50, 1.0, v50
	v_add_f32_e32 v51, 1.0, v51
	v_rcp_f32_e32 v50, v50
	v_rcp_f32_e32 v51, v51
	v_pk_mul_f32 v[44:45], v[44:45], v[48:49]
	v_pk_mul_f32 v[38:39], v[38:39], v[246:247] op_sel_hi:[1,0]
	v_pk_mul_f32 v[36:37], v[36:37], v[44:45]
	v_pk_mul_f32 v[44:45], v[46:47], v[50:51]
	v_exp_f32_e64 v46, -v40
	v_exp_f32_e64 v47, -v41
	v_pk_mul_f32 v[42:43], v[42:43], v[154:155] op_sel_hi:[1,0]
	v_pk_mul_f32 v[38:39], v[38:39], v[44:45]
	v_add_f32_e32 v44, 1.0, v46
	v_add_f32_e32 v45, 1.0, v47
	v_exp_f32_e64 v46, -v42
	v_exp_f32_e64 v47, -v43
	v_rcp_f32_e32 v44, v44
	v_rcp_f32_e32 v45, v45
	v_add_f32_e32 v46, 1.0, v46
	v_add_f32_e32 v47, 1.0, v47
	v_rcp_f32_e32 v46, v46
	v_rcp_f32_e32 v47, v47
	v_pk_mul_f32 v[40:41], v[40:41], v[44:45]
	v_pk_mul_f32 v[32:33], v[32:33], v[246:247] op_sel_hi:[1,0]
	v_pk_mul_f32 v[34:35], v[34:35], v[246:247] op_sel_hi:[1,0]
	v_pk_mul_f32 v[40:41], v[32:33], v[40:41]
	v_pk_mul_f32 v[32:33], v[42:43], v[46:47]
	v_pk_mul_f32 v[28:29], v[28:29], v[150:151] op_sel_hi:[1,0]
	v_pk_mul_f32 v[42:43], v[34:35], v[32:33]
	v_cvt_pk_bf16_f32 v32, v36, v37
	v_mad_i64_i32 v[36:37], s[38:39], v152, s49, v[112:113]
	v_cvt_pk_bf16_f32 v33, v38, v39
	v_cvt_pk_bf16_f32 v34, v40, v41
	v_cvt_pk_bf16_f32 v35, v42, v43
	v_lshl_add_u64 v[36:37], v[36:37], 0, v[114:115]
	v_pk_mul_f32 v[30:31], v[30:31], v[150:151] op_sel_hi:[1,0]
	v_exp_f32_e64 v38, -v28
	v_exp_f32_e64 v39, -v29
	global_store_dwordx4 v[36:37], v[32:35], off
	v_pk_mul_f32 v[20:21], v[20:21], v[248:249] op_sel_hi:[1,0]
	v_pk_mul_f32 v[24:25], v[24:25], v[150:151] op_sel_hi:[1,0]
	v_exp_f32_e64 v34, -v30
	v_exp_f32_e64 v35, -v31
	v_add_f32_e32 v32, 1.0, v38
	v_add_f32_e32 v33, 1.0, v39
	v_rcp_f32_e32 v32, v32
	v_rcp_f32_e32 v33, v33
	v_add_f32_e32 v34, 1.0, v34
	v_add_f32_e32 v35, 1.0, v35
	v_rcp_f32_e32 v34, v34
	v_rcp_f32_e32 v35, v35
	v_pk_mul_f32 v[28:29], v[28:29], v[32:33]
	v_pk_mul_f32 v[22:23], v[22:23], v[248:249] op_sel_hi:[1,0]
	v_pk_mul_f32 v[20:21], v[20:21], v[28:29]
	v_pk_mul_f32 v[28:29], v[30:31], v[34:35]
	v_exp_f32_e64 v30, -v24
	v_exp_f32_e64 v31, -v25
	v_pk_mul_f32 v[26:27], v[26:27], v[150:151] op_sel_hi:[1,0]
	v_pk_mul_f32 v[22:23], v[22:23], v[28:29]
	v_add_f32_e32 v28, 1.0, v30
	v_add_f32_e32 v29, 1.0, v31
	v_exp_f32_e64 v30, -v26
	v_exp_f32_e64 v31, -v27
	v_rcp_f32_e32 v28, v28
	v_rcp_f32_e32 v29, v29
	v_add_f32_e32 v30, 1.0, v30
	v_add_f32_e32 v31, 1.0, v31
	v_rcp_f32_e32 v30, v30
	v_rcp_f32_e32 v31, v31
	v_pk_mul_f32 v[24:25], v[24:25], v[28:29]
	v_pk_mul_f32 v[16:17], v[16:17], v[248:249] op_sel_hi:[1,0]
	v_pk_mul_f32 v[18:19], v[18:19], v[248:249] op_sel_hi:[1,0]
	v_pk_mul_f32 v[24:25], v[16:17], v[24:25]
	v_pk_mul_f32 v[16:17], v[26:27], v[30:31]
	v_pk_mul_f32 v[12:13], v[12:13], v[146:147] op_sel_hi:[1,0]
	v_pk_mul_f32 v[26:27], v[18:19], v[16:17]
	v_cvt_pk_bf16_f32 v16, v20, v21
	v_mad_i64_i32 v[20:21], s[38:39], v148, s49, v[112:113]
	v_cvt_pk_bf16_f32 v17, v22, v23
	v_cvt_pk_bf16_f32 v18, v24, v25
	v_cvt_pk_bf16_f32 v19, v26, v27
	v_lshl_add_u64 v[20:21], v[20:21], 0, v[114:115]
	v_pk_mul_f32 v[14:15], v[14:15], v[146:147] op_sel_hi:[1,0]
	v_exp_f32_e64 v22, -v12
	v_exp_f32_e64 v23, -v13
	global_store_dwordx4 v[20:21], v[16:19], off
	v_pk_mul_f32 v[4:5], v[4:5], v[250:251] op_sel_hi:[1,0]
	v_pk_mul_f32 v[8:9], v[8:9], v[146:147] op_sel_hi:[1,0]
	v_exp_f32_e64 v18, -v14
	v_exp_f32_e64 v19, -v15
	v_add_f32_e32 v16, 1.0, v22
	v_add_f32_e32 v17, 1.0, v23
	v_rcp_f32_e32 v16, v16
	v_rcp_f32_e32 v17, v17
	v_add_f32_e32 v18, 1.0, v18
	v_add_f32_e32 v19, 1.0, v19
	v_rcp_f32_e32 v18, v18
	v_rcp_f32_e32 v19, v19
	v_pk_mul_f32 v[12:13], v[12:13], v[16:17]
	v_pk_mul_f32 v[6:7], v[6:7], v[250:251] op_sel_hi:[1,0]
	v_pk_mul_f32 v[4:5], v[4:5], v[12:13]
	v_pk_mul_f32 v[12:13], v[14:15], v[18:19]
	v_exp_f32_e64 v14, -v8
	v_exp_f32_e64 v15, -v9
	v_pk_mul_f32 v[10:11], v[10:11], v[146:147] op_sel_hi:[1,0]
	v_pk_mul_f32 v[6:7], v[6:7], v[12:13]
	v_add_f32_e32 v12, 1.0, v14
	v_add_f32_e32 v13, 1.0, v15
	v_exp_f32_e64 v14, -v10
	v_exp_f32_e64 v15, -v11
	v_rcp_f32_e32 v12, v12
	v_rcp_f32_e32 v13, v13
	v_add_f32_e32 v14, 1.0, v14
	v_add_f32_e32 v15, 1.0, v15
	v_rcp_f32_e32 v14, v14
	v_rcp_f32_e32 v15, v15
	v_pk_mul_f32 v[8:9], v[8:9], v[12:13]
	v_pk_mul_f32 v[0:1], v[0:1], v[250:251] op_sel_hi:[1,0]
	v_pk_mul_f32 v[2:3], v[2:3], v[250:251] op_sel_hi:[1,0]
	v_pk_mul_f32 v[8:9], v[0:1], v[8:9]
	v_pk_mul_f32 v[0:1], v[10:11], v[14:15]
	s_nop 0
	v_pk_mul_f32 v[10:11], v[2:3], v[0:1]
	v_cvt_pk_bf16_f32 v0, v4, v5
	v_mad_i64_i32 v[4:5], s[38:39], v144, s49, v[112:113]
	v_cvt_pk_bf16_f32 v1, v6, v7
	v_cvt_pk_bf16_f32 v2, v8, v9
	v_cvt_pk_bf16_f32 v3, v10, v11
	v_lshl_add_u64 v[4:5], v[4:5], 0, v[114:115]
	global_store_dwordx4 v[4:5], v[0:3], off
	s_cbranch_vccnz .LBB0_1332
	s_andn2_b64 vcc, exec, s[10:11]
	s_cbranch_vccnz .LBB0_1331
	s_barrier
	s_branch .LBB0_1331
